# attention key loop: one static s_setprio 1 for waves 4-7 (reset to 0 after the loop)
# baseline (speedup 1.0000x reference)
; __device__ __forceinline__ void attn_item(const int tid, char* smem, const Params& p, int l, int item) {
;     ...
;   const int wid = tid >> 6, lane = tid & 63, fr = lane & 15, fq = lane >> 4;
;   int qt, bh;
;   if (item < 256) { const int x = item & 7, j = item >> 3; bh = x * 2 + (j >> 4); qt = 2 + (j & 15); }
;   else { const int r = item - 256, x = r & 7, j = r >> 3; bh = x * 2 + (j >> 1); qt = j & 1; }
;   const int hd = bh & 3, b = bh >> 2;
;   const int nkt = qt < 2 ? 4 : 36;
;   const bfu* Qc = reinterpret_cast<const bfu*>(p.ws + OFF_QC);
;   const bfu* Kc = reinterpret_cast<const bfu*>(p.ws + OFF_KC);
;   const bfu* Vt = reinterpret_cast<const bfu*>(p.ws + OFF_VT);
;   bfu* mix = reinterpret_cast<bfu*>(p.ws + OFF_MIX);
;   const float* lv = p.c_lambda + l * 256;
;   float d1 = wave_sum(lv[lane] * lv[64 + lane]);
;   float d2 = wave_sum(lv[128 + lane] * lv[192 + lane]);
;   const float lam_init = 0.8f - 0.6f * expf(-0.3f * (float)l);
;   const float lam = expf(d1) - expf(d2) + lam_init;
;   const int qrow = b * TPB + qt * 128 + wid * 16 + fr;
;   const bfu* qp = Qc + (size_t)qrow * 512 + hd * 128;
;   bf16x8 qf[2][2];
; #pragma unroll
;   for (int h = 0; h < 2; ++h)
; #pragma unroll
;     for (int ks = 0; ks < 2; ++ks) qf[h][ks] = *reinterpret_cast<const bf16x8*>(qp + h * 64 + ks * 32 + fq * 8);
;   f32x4 O[2][8];
; #pragma unroll
;   for (int h = 0; h < 2; ++h)
; #pragma unroll
;     for (int vb = 0; vb < 8; ++vb) O[h][vb] = (f32x4){0.f, 0.f, 0.f, 0.f};
;   float mrun[2] = {-INFINITY, -INFINITY}, lrun[2] = {0.f, 0.f};
;   const bfu* kbase = Kc + (size_t)(b * TPB) * 512 + hd * 128;
;   const bfu* vbase = Vt + ((size_t)b * 512 + hd * 128) * TPB;
;   const unsigned koff0 = (unsigned)((tid >> 4) * 512 + (tid & 15) * 8), koff1 = koff0 + 32u * 512u;
;   const unsigned voff0 = (unsigned)((tid >> 3) * TPB + (tid & 7) * 8), voff1 = voff0 + 64u * (unsigned)TPB;
;   const int kl0 = (tid >> 4) * 288 + (tid & 15) * 16;
;   const int vq = tid & 7;
;   const int vl0 = (tid >> 3) * 288 + ((vq >> 2) * 32 + 2 * (vq & 1) * 8 + ((vq >> 1) & 1) * 4) * 2;
;   constexpr int ABUF = 55296;
; __device__ __forceinline__ void phase_m1(const int tid512, char* smem, const Params& p, int l) {
;     ...
;     const int tid = opaque(tid512);
; #pragma unroll 1
;     for (int it = blockIdx.x; it < N_ATT; it += gridDim.x) attn_item(tid, smem, p, l, it);
.LBB0_86:
	s_mov_b64 s[2:3], 0
	v_writelane_b32 v255, s2, 19
	s_mov_b32 s29, 0x3e800000
	s_nop 0
	v_writelane_b32 v255, s3, 20
	s_cbranch_execz .LBB0_341
	s_cmp_gt_i32 s75, 2
	s_mov_b64 s[0:1], -1
	s_cbranch_scc0 .LBB0_795
	s_cmp_gt_i32 s75, 3
	s_cbranch_scc0 .LBB0_343
	s_cmp_eq_u32 s40, 1
	s_movk_i32 s0, 0x120
	s_cselect_b32 s6, 0x100, s0
	v_readlane_b32 s0, v252, 0
	s_waitcnt vmcnt(0)
	v_mov_b32_e32 v0, v198
	s_cmp_ge_i32 s0, s6
	s_cbranch_scc1 .LBB0_106
	v_readfirstlane_b32 s0, v198
	s_nop 3
	s_lshr_b32 s0, s0, 8
	s_cmp_lg_u32 s0, 0
	s_cbranch_scc0 .Latt_prio_done
	s_setprio 1
.Latt_prio_done:
	v_and_b32_e32 v2, 64, v186
	v_add_u32_e32 v2, 64, v2
	v_xor_b32_e32 v4, 32, v186
	v_cmp_lt_i32_e32 vcc, v4, v2
	v_and_b32_e32 v3, 15, v0
	v_ashrrev_i32_e32 v7, 3, v0
	v_cndmask_b32_e32 v4, v186, v4, vcc
	v_lshlrev_b32_e32 v153, 2, v4
	v_xor_b32_e32 v4, 16, v186
	v_cmp_lt_i32_e32 vcc, v4, v2
	s_movk_i32 s0, 0x900
	v_ashrrev_i32_e32 v5, 4, v0
	v_cndmask_b32_e32 v4, v186, v4, vcc
	v_lshlrev_b32_e32 v172, 2, v4
	v_xor_b32_e32 v4, 8, v186
	v_cmp_lt_i32_e32 vcc, v4, v2
	v_mul_lo_u32 v9, v7, s0
	v_and_b32_e32 v10, 7, v0
	v_cndmask_b32_e32 v4, v186, v4, vcc
	v_lshlrev_b32_e32 v173, 2, v4
	v_xor_b32_e32 v4, 4, v186
	v_cmp_lt_i32_e32 vcc, v4, v2
	s_movk_i32 s0, 0x120
	v_cvt_f32_u32_e32 v15, s40
	v_cndmask_b32_e32 v4, v186, v4, vcc
	v_lshlrev_b32_e32 v203, 2, v4
	v_xor_b32_e32 v4, 2, v186
	v_cmp_lt_i32_e32 vcc, v4, v2
	v_lshl_or_b32 v132, v10, 3, v9
	v_mul_lo_u32 v9, v5, s0
	v_cndmask_b32_e32 v4, v186, v4, vcc
	v_lshlrev_b32_e32 v204, 2, v4
	v_xor_b32_e32 v4, 1, v186
	v_cmp_lt_i32_e32 vcc, v4, v2
	v_lshlrev_b32_e32 v10, 4, v3
	v_add3_u32 v207, 0, v9, v10
	v_cndmask_b32_e32 v2, v186, v4, vcc
	v_lshlrev_b32_e32 v4, 3, v3
	v_lshl_or_b32 v4, v5, 9, v4
	v_lshlrev_b32_e32 v5, 4, v0
	v_and_b32_e32 v12, 64, v5
	v_lshlrev_b32_e32 v5, 5, v0
	v_and_b32_e32 v13, 32, v5
	v_lshlrev_b32_e32 v5, 2, v0
	v_and_b32_e32 v14, 8, v5
	v_mul_f32_e32 v10, 0xbe99999a, v15
	v_mul_lo_u32 v11, v7, s0
	v_add3_u32 v9, 0, v14, v13
	v_mul_f32_e32 v13, 0x3fb8aa3b, v10
	s_mov_b32 s0, 0x3fb8aa3b
	v_fma_f32 v14, v10, s0, -v13
	v_rndne_f32_e32 v15, v13
	v_fmac_f32_e32 v14, 0x32a5705f, v10
	v_sub_f32_e32 v13, v13, v15
	v_add_f32_e32 v13, v13, v14
	v_exp_f32_e32 v13, v13
	v_cvt_i32_f32_e32 v14, v15
	s_mov_b32 s0, 0xc2ce8ed0
	s_lshl_b32 s92, s40, 8
	v_add3_u32 v208, v9, v12, v11
	v_ldexp_f32 v9, v13, v14
	v_cmp_ngt_f32_e32 vcc, s0, v10
	s_mov_b32 s0, 0x42b17218
	v_readlane_b32 s72, v254, 9
	v_cndmask_b32_e32 v9, 0, v9, vcc
	v_cmp_nlt_f32_e32 vcc, s0, v10
	s_lshl_b32 s0, s40, 7
	s_lshl_b64 s[2:3], s[92:93], 2
	v_readlane_b32 s86, v254, 23
	s_mov_b32 s1, s93
	v_readlane_b32 s73, v254, 10
	v_readlane_b32 s74, v254, 11
	v_readlane_b32 s75, v254, 12
	v_readlane_b32 s76, v254, 13
	v_readlane_b32 s77, v254, 14
	v_readlane_b32 s78, v254, 15
	v_readlane_b32 s79, v254, 16
	v_readlane_b32 s80, v254, 17
	v_readlane_b32 s81, v254, 18
	v_readlane_b32 s82, v254, 19
	v_readlane_b32 s83, v254, 20
	v_readlane_b32 s84, v254, 21
	v_readlane_b32 s85, v254, 22
	v_readlane_b32 s87, v254, 24
	s_add_u32 s2, s86, s2
	s_addc_u32 s3, s87, s3
	s_lshl_b64 s[0:1], s[0:1], 2
	v_readlane_b32 s72, v254, 25
	v_and_b32_e32 v1, 63, v0
	v_lshlrev_b32_e32 v205, 2, v2
	v_ashrrev_i32_e32 v2, 2, v0
	v_cndmask_b32_e32 v9, v188, v9, vcc
	v_mov_b32_e32 v10, 0x3f4ccccd
	v_readlane_b32 s73, v254, 26
	s_add_u32 s0, s72, s0
	v_bfe_u32 v8, v0, 4, 2
	v_bfi_b32 v206, -16, v2, v0
	v_and_b32_e32 v0, 48, v0
	v_mul_u32_u24_e32 v3, 0x120, v3
	v_fmamk_f32 v209, v9, 0xbf19999a, v10
	v_lshlrev_b32_e32 v10, 2, v1
	s_addc_u32 s1, s73, s1
	v_mov_b32_e32 v1, v18
	v_add_u32_e32 v6, 0x4000, v4
	v_mov_b32_e32 v5, v18
	v_mov_b32_e32 v7, v18
	v_lshl_add_u64 v[138:139], s[0:1], 0, v[0:1]
	v_add3_u32 v211, 0, v0, v3
	v_mov_b64_e32 v[0:1], 0x2c794000
	v_lshlrev_b32_e32 v2, 3, v8
	v_add_u32_e32 v134, 0x24000, v132
	v_mov_b32_e32 v133, v18
	v_mov_b32_e32 v135, v18
	v_lshlrev_b32_e32 v8, 2, v8
	v_mov_b32_e32 v11, v18
	v_lshl_add_u64 v[140:141], v[4:5], 1, v[0:1]
	v_lshl_add_u64 v[142:143], v[6:7], 1, v[0:1]
	v_mov_b64_e32 v[0:1], 0x2d074100
	v_sub_f32_e32 v210, 1.0, v209
	v_lshl_add_u64 v[136:137], s[2:3], 0, v[10:11]
	v_lshl_add_u64 v[144:145], v[132:133], 1, v[0:1]
	v_lshl_add_u64 v[146:147], v[134:135], 1, v[0:1]
	v_lshlrev_b32_e32 v154, 1, v2
	v_lshlrev_b64 v[156:157], 1, v[4:5]
	v_lshlrev_b64 v[158:159], 1, v[6:7]
	v_lshlrev_b32_e32 v160, 1, v8
	v_readlane_b32 s7, v252, 0
	v_readlane_b32 s74, v254, 27
	v_readlane_b32 s75, v254, 28
	v_readlane_b32 s76, v254, 29
	v_readlane_b32 s77, v254, 30
	v_readlane_b32 s78, v254, 31
	v_readlane_b32 s79, v254, 32
	v_readlane_b32 s80, v254, 33
	v_readlane_b32 s81, v254, 34
	v_readlane_b32 s82, v254, 35
	v_readlane_b32 s83, v254, 36
	v_readlane_b32 s84, v254, 37
	v_readlane_b32 s85, v254, 38
	v_readlane_b32 s86, v254, 39
	v_readlane_b32 s87, v254, 40

; __device__ __forceinline__ int opaque(int v) { asm volatile("" : "+v"(v)); return v; }
; __device__ __forceinline__ void phase_m1(const int tid512, char* smem, const Params& p, int l) {
;     ...
;   const int VG = 2 * (int)gridDim.x;
;   {
;     Ctx cx; cx.tid = opaque(tid512) & 255; cx.vb = 2 * blockIdx.x + half; cx.vg = VG; cx.lds = smem + half * 65536;
;     const int wid = cx.tid >> 6, lane = cx.tid & 63;
;     int b0 = cx.vb - 64; if (b0 < 0) b0 += VG;
; #pragma unroll 1
;     for (int it = b0; it < N_GLA; it += VG) gla_pass1(cx, p, l, it * 4 + wid, reinterpret_cast<float*>(cx.lds) + wid * 4096, lane);
.LBB0_106:
	s_setprio 0
	v_mov_b32_e32 v1, s42
	v_cmp_gt_i32_e32 vcc, 64, v202
	s_movk_i32 s0, 0xffc0
	v_mov_b32_e32 v0, v198
	v_cndmask_b32_e32 v1, 0, v1, vcc
	v_add3_u32 v130, v202, v1, s0
	s_movk_i32 s0, 0x480
	v_cmp_gt_i32_e32 vcc, s0, v130
	s_and_saveexec_b64 s[12:13], vcc
	s_cbranch_execz .LBB0_142
	v_bfe_u32 v131, v0, 6, 2
	v_and_b32_e32 v132, 63, v0
	v_and_b32_e32 v3, 15, v0
	v_lshrrev_b32_e32 v0, 1, v0
	v_lshl_add_u32 v1, v131, 14, v197
	v_and_b32_e32 v112, 24, v0
	v_add_u32_e32 v134, v1, v112
	v_mul_u32_u24_e32 v0, 20, v3
	v_lshl_add_u32 v135, v0, 1, v134
	v_or_b32_e32 v0, 48, v132
	v_readlane_b32 s0, v252, 29
	v_lshlrev_b32_e32 v2, 2, v132
	v_mul_u32_u24_e32 v0, 20, v0
	v_mov_b32_e32 v113, v18
	v_readlane_b32 s1, v252, 30
	v_add_u32_e32 v133, v1, v2
	v_lshl_add_u32 v1, v0, 1, v134
	v_lshlrev_b32_e32 v0, 6, v3
	v_lshl_add_u64 v[114:115], s[0:1], 0, v[112:113]
	v_readlane_b32 s0, v252, 39
	v_mul_u32_u24_e32 v5, 36, v132
	v_or_b32_e32 v4, 0x800, v0
	v_or_b32_e32 v6, 0xc00, v0
	v_mov_b32_e32 v3, v18
	v_readlane_b32 s1, v252, 40
	s_mov_b64 s[14:15], 0
	v_add_u32_e32 v113, v133, v5
	v_lshl_add_u64 v[116:117], s[0:1], 0, v[2:3]
	v_lshlrev_b32_e32 v118, 1, v0
	v_lshlrev_b32_e32 v120, 1, v4
	v_lshlrev_b32_e32 v122, 1, v6
	v_add_u32_e32 v136, 0x100, v1
	s_branch .LBB0_109
